# rendezvous off + P0 silu table: 40 loads issued up front instead of 40 serialized round trips
# speedup vs baseline: 1.0104x; 1.0104x over previous
.Lsilu_batch:
	global_load_dword v8, v2, s[62:63]
	global_load_dword v9, v2, s[62:63] offset:2048
	s_add_u32 s2, s62, 0x1000
	s_addc_u32 s3, s63, 0
	global_load_dword v10, v2, s[2:3]
	global_load_dword v11, v2, s[2:3] offset:2048
	s_add_u32 s2, s62, 0x2000
	s_addc_u32 s3, s63, 0
	global_load_dword v12, v2, s[2:3]
	global_load_dword v13, v2, s[2:3] offset:2048
	s_add_u32 s2, s62, 0x3000
	s_addc_u32 s3, s63, 0
	global_load_dword v14, v2, s[2:3]
	global_load_dword v15, v2, s[2:3] offset:2048
	global_load_dword v16, v2, s[60:61]
	global_load_dword v17, v2, s[60:61] offset:2048
	s_add_u32 s2, s60, 0x1000
	s_addc_u32 s3, s61, 0
	global_load_dword v18, v2, s[2:3]
	global_load_dword v19, v2, s[2:3] offset:2048
	s_add_u32 s2, s60, 0x2000
	s_addc_u32 s3, s61, 0
	global_load_dword v20, v2, s[2:3]
	global_load_dword v21, v2, s[2:3] offset:2048
	s_add_u32 s2, s60, 0x3000
	s_addc_u32 s3, s61, 0
	global_load_dword v22, v2, s[2:3]
	global_load_dword v23, v2, s[2:3] offset:2048
	s_add_u32 s2, s60, 0x4000
	s_addc_u32 s3, s61, 0
	global_load_dword v24, v2, s[2:3]
	global_load_dword v25, v2, s[2:3] offset:2048
	s_add_u32 s2, s60, 0x5000
	s_addc_u32 s3, s61, 0
	global_load_dword v26, v2, s[2:3]
	global_load_dword v27, v2, s[2:3] offset:2048
	s_add_u32 s2, s60, 0x6000
	s_addc_u32 s3, s61, 0
	global_load_dword v28, v2, s[2:3]
	global_load_dword v29, v2, s[2:3] offset:2048
	s_add_u32 s2, s60, 0x7000
	s_addc_u32 s3, s61, 0
	global_load_dword v30, v2, s[2:3]
	global_load_dword v31, v2, s[2:3] offset:2048
	s_add_u32 s2, s60, 0x8000
	s_addc_u32 s3, s61, 0
	global_load_dword v32, v2, s[2:3]
	global_load_dword v33, v2, s[2:3] offset:2048
	s_add_u32 s2, s60, 0x9000
	s_addc_u32 s3, s61, 0
	global_load_dword v34, v2, s[2:3]
	global_load_dword v35, v2, s[2:3] offset:2048
	s_add_u32 s2, s60, 0xa000
	s_addc_u32 s3, s61, 0
	global_load_dword v36, v2, s[2:3]
	global_load_dword v37, v2, s[2:3] offset:2048
	s_add_u32 s2, s60, 0xb000
	s_addc_u32 s3, s61, 0
	global_load_dword v38, v2, s[2:3]
	global_load_dword v39, v2, s[2:3] offset:2048
	s_add_u32 s2, s60, 0xc000
	s_addc_u32 s3, s61, 0
	global_load_dword v40, v2, s[2:3]
	global_load_dword v41, v2, s[2:3] offset:2048
	s_add_u32 s2, s60, 0xd000
	s_addc_u32 s3, s61, 0
	global_load_dword v42, v2, s[2:3]
	global_load_dword v43, v2, s[2:3] offset:2048
	s_add_u32 s2, s60, 0xe000
	s_addc_u32 s3, s61, 0
	global_load_dword v44, v2, s[2:3]
	global_load_dword v45, v2, s[2:3] offset:2048
	s_add_u32 s2, s60, 0xf000
	s_addc_u32 s3, s61, 0
	global_load_dword v46, v2, s[2:3]
	global_load_dword v47, v2, s[2:3] offset:2048
	v_add_u32_e32 v3, 0x10000, v2
	s_waitcnt vmcnt(39)
	v_mul_f32_e32 v50, 0xbfb8aa3b, v8
	v_exp_f32_e32 v50, v50
	s_nop 0
	v_add_f32_e32 v50, 1.0, v50
	v_div_scale_f32 v51, s[8:9], v50, v50, v8
	v_rcp_f32_e32 v52, v51
	v_div_scale_f32 v53, vcc, v8, v50, v8
	v_fma_f32 v54, -v51, v52, 1.0
	v_fmac_f32_e32 v52, v54, v52
	v_mul_f32_e32 v54, v53, v52
	v_fma_f32 v55, -v51, v54, v53
	v_fmac_f32_e32 v54, v55, v52
	v_fma_f32 v51, -v51, v54, v53
	v_div_fmas_f32 v51, v51, v52, v54
	v_div_fixup_f32 v8, v51, v50, v8
	ds_write_b32 v2, v8
	s_waitcnt vmcnt(38)
	v_mul_f32_e32 v50, 0xbfb8aa3b, v9
	v_exp_f32_e32 v50, v50
	s_nop 0
	v_add_f32_e32 v50, 1.0, v50
	v_div_scale_f32 v51, s[8:9], v50, v50, v9
	v_rcp_f32_e32 v52, v51
	v_div_scale_f32 v53, vcc, v9, v50, v9
	v_fma_f32 v54, -v51, v52, 1.0
	v_fmac_f32_e32 v52, v54, v52
	v_mul_f32_e32 v54, v53, v52
	v_fma_f32 v55, -v51, v54, v53
	v_fmac_f32_e32 v54, v55, v52
	v_fma_f32 v51, -v51, v54, v53
	v_div_fmas_f32 v51, v51, v52, v54
	v_div_fixup_f32 v9, v51, v50, v9
	ds_write_b32 v2, v9 offset:2048
	s_waitcnt vmcnt(37)
	v_mul_f32_e32 v50, 0xbfb8aa3b, v10
	v_exp_f32_e32 v50, v50
	s_nop 0
	v_add_f32_e32 v50, 1.0, v50
	v_div_scale_f32 v51, s[8:9], v50, v50, v10
	v_rcp_f32_e32 v52, v51
	v_div_scale_f32 v53, vcc, v10, v50, v10
	v_fma_f32 v54, -v51, v52, 1.0
	v_fmac_f32_e32 v52, v54, v52
	v_mul_f32_e32 v54, v53, v52
	v_fma_f32 v55, -v51, v54, v53
	v_fmac_f32_e32 v54, v55, v52
	v_fma_f32 v51, -v51, v54, v53
	v_div_fmas_f32 v51, v51, v52, v54
	v_div_fixup_f32 v10, v51, v50, v10
	ds_write_b32 v2, v10 offset:4096
	s_waitcnt vmcnt(36)
	v_mul_f32_e32 v50, 0xbfb8aa3b, v11
	v_exp_f32_e32 v50, v50
	s_nop 0
	v_add_f32_e32 v50, 1.0, v50
	v_div_scale_f32 v51, s[8:9], v50, v50, v11
	v_rcp_f32_e32 v52, v51
	v_div_scale_f32 v53, vcc, v11, v50, v11
	v_fma_f32 v54, -v51, v52, 1.0
	v_fmac_f32_e32 v52, v54, v52
	v_mul_f32_e32 v54, v53, v52
	v_fma_f32 v55, -v51, v54, v53
	v_fmac_f32_e32 v54, v55, v52
	v_fma_f32 v51, -v51, v54, v53
	v_div_fmas_f32 v51, v51, v52, v54
	v_div_fixup_f32 v11, v51, v50, v11
	ds_write_b32 v2, v11 offset:6144
	s_waitcnt vmcnt(35)
	v_mul_f32_e32 v50, 0xbfb8aa3b, v12
	v_exp_f32_e32 v50, v50
	s_nop 0
	v_add_f32_e32 v50, 1.0, v50
	v_div_scale_f32 v51, s[8:9], v50, v50, v12
	v_rcp_f32_e32 v52, v51
	v_div_scale_f32 v53, vcc, v12, v50, v12
	v_fma_f32 v54, -v51, v52, 1.0
	v_fmac_f32_e32 v52, v54, v52
	v_mul_f32_e32 v54, v53, v52
	v_fma_f32 v55, -v51, v54, v53
	v_fmac_f32_e32 v54, v55, v52
	v_fma_f32 v51, -v51, v54, v53
	v_div_fmas_f32 v51, v51, v52, v54
	v_div_fixup_f32 v12, v51, v50, v12
	ds_write_b32 v2, v12 offset:8192
	s_waitcnt vmcnt(34)
	v_mul_f32_e32 v50, 0xbfb8aa3b, v13
	v_exp_f32_e32 v50, v50
	s_nop 0
	v_add_f32_e32 v50, 1.0, v50
	v_div_scale_f32 v51, s[8:9], v50, v50, v13
	v_rcp_f32_e32 v52, v51
	v_div_scale_f32 v53, vcc, v13, v50, v13
	v_fma_f32 v54, -v51, v52, 1.0
	v_fmac_f32_e32 v52, v54, v52
	v_mul_f32_e32 v54, v53, v52
	v_fma_f32 v55, -v51, v54, v53
	v_fmac_f32_e32 v54, v55, v52
	v_fma_f32 v51, -v51, v54, v53
	v_div_fmas_f32 v51, v51, v52, v54
	v_div_fixup_f32 v13, v51, v50, v13
	ds_write_b32 v2, v13 offset:10240
	s_waitcnt vmcnt(33)
	v_mul_f32_e32 v50, 0xbfb8aa3b, v14
	v_exp_f32_e32 v50, v50
	s_nop 0
	v_add_f32_e32 v50, 1.0, v50
	v_div_scale_f32 v51, s[8:9], v50, v50, v14
	v_rcp_f32_e32 v52, v51
	v_div_scale_f32 v53, vcc, v14, v50, v14
	v_fma_f32 v54, -v51, v52, 1.0
	v_fmac_f32_e32 v52, v54, v52
	v_mul_f32_e32 v54, v53, v52
	v_fma_f32 v55, -v51, v54, v53
	v_fmac_f32_e32 v54, v55, v52
	v_fma_f32 v51, -v51, v54, v53
	v_div_fmas_f32 v51, v51, v52, v54
	v_div_fixup_f32 v14, v51, v50, v14
	ds_write_b32 v2, v14 offset:12288
	s_waitcnt vmcnt(32)
	v_mul_f32_e32 v50, 0xbfb8aa3b, v15
	v_exp_f32_e32 v50, v50
	s_nop 0
	v_add_f32_e32 v50, 1.0, v50
	v_div_scale_f32 v51, s[8:9], v50, v50, v15
	v_rcp_f32_e32 v52, v51
	v_div_scale_f32 v53, vcc, v15, v50, v15
	v_fma_f32 v54, -v51, v52, 1.0
	v_fmac_f32_e32 v52, v54, v52
	v_mul_f32_e32 v54, v53, v52
	v_fma_f32 v55, -v51, v54, v53
	v_fmac_f32_e32 v54, v55, v52
	v_fma_f32 v51, -v51, v54, v53
	v_div_fmas_f32 v51, v51, v52, v54
	v_div_fixup_f32 v15, v51, v50, v15
	ds_write_b32 v2, v15 offset:14336
	s_waitcnt vmcnt(31)
	v_mul_f32_e32 v50, 0xbfb8aa3b, v16
	v_exp_f32_e32 v50, v50
	s_nop 0
	v_add_f32_e32 v50, 1.0, v50
	v_div_scale_f32 v51, s[8:9], v50, v50, v16
	v_rcp_f32_e32 v52, v51
	v_div_scale_f32 v53, vcc, v16, v50, v16
	v_fma_f32 v54, -v51, v52, 1.0
	v_fmac_f32_e32 v52, v54, v52
	v_mul_f32_e32 v54, v53, v52
	v_fma_f32 v55, -v51, v54, v53
	v_fmac_f32_e32 v54, v55, v52
	v_fma_f32 v51, -v51, v54, v53
	v_div_fmas_f32 v51, v51, v52, v54
	v_div_fixup_f32 v16, v51, v50, v16
	ds_write_b32 v2, v16 offset:16384
	s_waitcnt vmcnt(30)
	v_mul_f32_e32 v50, 0xbfb8aa3b, v17
	v_exp_f32_e32 v50, v50
	s_nop 0
	v_add_f32_e32 v50, 1.0, v50
	v_div_scale_f32 v51, s[8:9], v50, v50, v17
	v_rcp_f32_e32 v52, v51
	v_div_scale_f32 v53, vcc, v17, v50, v17
	v_fma_f32 v54, -v51, v52, 1.0
	v_fmac_f32_e32 v52, v54, v52
	v_mul_f32_e32 v54, v53, v52
	v_fma_f32 v55, -v51, v54, v53
	v_fmac_f32_e32 v54, v55, v52
	v_fma_f32 v51, -v51, v54, v53
	v_div_fmas_f32 v51, v51, v52, v54
	v_div_fixup_f32 v17, v51, v50, v17
	ds_write_b32 v2, v17 offset:18432
	s_waitcnt vmcnt(29)
	v_mul_f32_e32 v50, 0xbfb8aa3b, v18
	v_exp_f32_e32 v50, v50
	s_nop 0
	v_add_f32_e32 v50, 1.0, v50
	v_div_scale_f32 v51, s[8:9], v50, v50, v18
	v_rcp_f32_e32 v52, v51
	v_div_scale_f32 v53, vcc, v18, v50, v18
	v_fma_f32 v54, -v51, v52, 1.0
	v_fmac_f32_e32 v52, v54, v52
	v_mul_f32_e32 v54, v53, v52
	v_fma_f32 v55, -v51, v54, v53
	v_fmac_f32_e32 v54, v55, v52
	v_fma_f32 v51, -v51, v54, v53
	v_div_fmas_f32 v51, v51, v52, v54
	v_div_fixup_f32 v18, v51, v50, v18
	ds_write_b32 v2, v18 offset:20480
	s_waitcnt vmcnt(28)
	v_mul_f32_e32 v50, 0xbfb8aa3b, v19
	v_exp_f32_e32 v50, v50
	s_nop 0
	v_add_f32_e32 v50, 1.0, v50
	v_div_scale_f32 v51, s[8:9], v50, v50, v19
	v_rcp_f32_e32 v52, v51
	v_div_scale_f32 v53, vcc, v19, v50, v19
	v_fma_f32 v54, -v51, v52, 1.0
	v_fmac_f32_e32 v52, v54, v52
	v_mul_f32_e32 v54, v53, v52
	v_fma_f32 v55, -v51, v54, v53
	v_fmac_f32_e32 v54, v55, v52
	v_fma_f32 v51, -v51, v54, v53
	v_div_fmas_f32 v51, v51, v52, v54
	v_div_fixup_f32 v19, v51, v50, v19
	ds_write_b32 v2, v19 offset:22528
	s_waitcnt vmcnt(27)
	v_mul_f32_e32 v50, 0xbfb8aa3b, v20
	v_exp_f32_e32 v50, v50
	s_nop 0
	v_add_f32_e32 v50, 1.0, v50
	v_div_scale_f32 v51, s[8:9], v50, v50, v20
	v_rcp_f32_e32 v52, v51
	v_div_scale_f32 v53, vcc, v20, v50, v20
	v_fma_f32 v54, -v51, v52, 1.0
	v_fmac_f32_e32 v52, v54, v52
	v_mul_f32_e32 v54, v53, v52
	v_fma_f32 v55, -v51, v54, v53
	v_fmac_f32_e32 v54, v55, v52
	v_fma_f32 v51, -v51, v54, v53
	v_div_fmas_f32 v51, v51, v52, v54
	v_div_fixup_f32 v20, v51, v50, v20
	ds_write_b32 v2, v20 offset:24576
	s_waitcnt vmcnt(26)
	v_mul_f32_e32 v50, 0xbfb8aa3b, v21
	v_exp_f32_e32 v50, v50
	s_nop 0
	v_add_f32_e32 v50, 1.0, v50
	v_div_scale_f32 v51, s[8:9], v50, v50, v21
	v_rcp_f32_e32 v52, v51
	v_div_scale_f32 v53, vcc, v21, v50, v21
	v_fma_f32 v54, -v51, v52, 1.0
	v_fmac_f32_e32 v52, v54, v52
	v_mul_f32_e32 v54, v53, v52
	v_fma_f32 v55, -v51, v54, v53
	v_fmac_f32_e32 v54, v55, v52
	v_fma_f32 v51, -v51, v54, v53
	v_div_fmas_f32 v51, v51, v52, v54
	v_div_fixup_f32 v21, v51, v50, v21
	ds_write_b32 v2, v21 offset:26624
	s_waitcnt vmcnt(25)
	v_mul_f32_e32 v50, 0xbfb8aa3b, v22
	v_exp_f32_e32 v50, v50
	s_nop 0
	v_add_f32_e32 v50, 1.0, v50
	v_div_scale_f32 v51, s[8:9], v50, v50, v22
	v_rcp_f32_e32 v52, v51
	v_div_scale_f32 v53, vcc, v22, v50, v22
	v_fma_f32 v54, -v51, v52, 1.0
	v_fmac_f32_e32 v52, v54, v52
	v_mul_f32_e32 v54, v53, v52
	v_fma_f32 v55, -v51, v54, v53
	v_fmac_f32_e32 v54, v55, v52
	v_fma_f32 v51, -v51, v54, v53
	v_div_fmas_f32 v51, v51, v52, v54
	v_div_fixup_f32 v22, v51, v50, v22
	ds_write_b32 v2, v22 offset:28672
	s_waitcnt vmcnt(24)
	v_mul_f32_e32 v50, 0xbfb8aa3b, v23
	v_exp_f32_e32 v50, v50
	s_nop 0
	v_add_f32_e32 v50, 1.0, v50
	v_div_scale_f32 v51, s[8:9], v50, v50, v23
	v_rcp_f32_e32 v52, v51
	v_div_scale_f32 v53, vcc, v23, v50, v23
	v_fma_f32 v54, -v51, v52, 1.0
	v_fmac_f32_e32 v52, v54, v52
	v_mul_f32_e32 v54, v53, v52
	v_fma_f32 v55, -v51, v54, v53
	v_fmac_f32_e32 v54, v55, v52
	v_fma_f32 v51, -v51, v54, v53
	v_div_fmas_f32 v51, v51, v52, v54
	v_div_fixup_f32 v23, v51, v50, v23
	ds_write_b32 v2, v23 offset:30720
	s_waitcnt vmcnt(23)
	v_mul_f32_e32 v50, 0xbfb8aa3b, v24
	v_exp_f32_e32 v50, v50
	s_nop 0
	v_add_f32_e32 v50, 1.0, v50
	v_div_scale_f32 v51, s[8:9], v50, v50, v24
	v_rcp_f32_e32 v52, v51
	v_div_scale_f32 v53, vcc, v24, v50, v24
	v_fma_f32 v54, -v51, v52, 1.0
	v_fmac_f32_e32 v52, v54, v52
	v_mul_f32_e32 v54, v53, v52
	v_fma_f32 v55, -v51, v54, v53
	v_fmac_f32_e32 v54, v55, v52
	v_fma_f32 v51, -v51, v54, v53
	v_div_fmas_f32 v51, v51, v52, v54
	v_div_fixup_f32 v24, v51, v50, v24
	ds_write_b32 v2, v24 offset:32768
	s_waitcnt vmcnt(22)
	v_mul_f32_e32 v50, 0xbfb8aa3b, v25
	v_exp_f32_e32 v50, v50
	s_nop 0
	v_add_f32_e32 v50, 1.0, v50
	v_div_scale_f32 v51, s[8:9], v50, v50, v25
	v_rcp_f32_e32 v52, v51
	v_div_scale_f32 v53, vcc, v25, v50, v25
	v_fma_f32 v54, -v51, v52, 1.0
	v_fmac_f32_e32 v52, v54, v52
	v_mul_f32_e32 v54, v53, v52
	v_fma_f32 v55, -v51, v54, v53
	v_fmac_f32_e32 v54, v55, v52
	v_fma_f32 v51, -v51, v54, v53
	v_div_fmas_f32 v51, v51, v52, v54
	v_div_fixup_f32 v25, v51, v50, v25
	ds_write_b32 v2, v25 offset:34816
	s_waitcnt vmcnt(21)
	v_mul_f32_e32 v50, 0xbfb8aa3b, v26
	v_exp_f32_e32 v50, v50
	s_nop 0
	v_add_f32_e32 v50, 1.0, v50
	v_div_scale_f32 v51, s[8:9], v50, v50, v26
	v_rcp_f32_e32 v52, v51
	v_div_scale_f32 v53, vcc, v26, v50, v26
	v_fma_f32 v54, -v51, v52, 1.0
	v_fmac_f32_e32 v52, v54, v52
	v_mul_f32_e32 v54, v53, v52
	v_fma_f32 v55, -v51, v54, v53
	v_fmac_f32_e32 v54, v55, v52
	v_fma_f32 v51, -v51, v54, v53
	v_div_fmas_f32 v51, v51, v52, v54
	v_div_fixup_f32 v26, v51, v50, v26
	ds_write_b32 v2, v26 offset:36864
	s_waitcnt vmcnt(20)
	v_mul_f32_e32 v50, 0xbfb8aa3b, v27
	v_exp_f32_e32 v50, v50
	s_nop 0
	v_add_f32_e32 v50, 1.0, v50
	v_div_scale_f32 v51, s[8:9], v50, v50, v27
	v_rcp_f32_e32 v52, v51
	v_div_scale_f32 v53, vcc, v27, v50, v27
	v_fma_f32 v54, -v51, v52, 1.0
	v_fmac_f32_e32 v52, v54, v52
	v_mul_f32_e32 v54, v53, v52
	v_fma_f32 v55, -v51, v54, v53
	v_fmac_f32_e32 v54, v55, v52
	v_fma_f32 v51, -v51, v54, v53
	v_div_fmas_f32 v51, v51, v52, v54
	v_div_fixup_f32 v27, v51, v50, v27
	ds_write_b32 v2, v27 offset:38912
	s_waitcnt vmcnt(19)
	v_mul_f32_e32 v50, 0xbfb8aa3b, v28
	v_exp_f32_e32 v50, v50
	s_nop 0
	v_add_f32_e32 v50, 1.0, v50
	v_div_scale_f32 v51, s[8:9], v50, v50, v28
	v_rcp_f32_e32 v52, v51
	v_div_scale_f32 v53, vcc, v28, v50, v28
	v_fma_f32 v54, -v51, v52, 1.0
	v_fmac_f32_e32 v52, v54, v52
	v_mul_f32_e32 v54, v53, v52
	v_fma_f32 v55, -v51, v54, v53
	v_fmac_f32_e32 v54, v55, v52
	v_fma_f32 v51, -v51, v54, v53
	v_div_fmas_f32 v51, v51, v52, v54
	v_div_fixup_f32 v28, v51, v50, v28
	ds_write_b32 v2, v28 offset:40960
	s_waitcnt vmcnt(18)
	v_mul_f32_e32 v50, 0xbfb8aa3b, v29
	v_exp_f32_e32 v50, v50
	s_nop 0
	v_add_f32_e32 v50, 1.0, v50
	v_div_scale_f32 v51, s[8:9], v50, v50, v29
	v_rcp_f32_e32 v52, v51
	v_div_scale_f32 v53, vcc, v29, v50, v29
	v_fma_f32 v54, -v51, v52, 1.0
	v_fmac_f32_e32 v52, v54, v52
	v_mul_f32_e32 v54, v53, v52
	v_fma_f32 v55, -v51, v54, v53
	v_fmac_f32_e32 v54, v55, v52
	v_fma_f32 v51, -v51, v54, v53
	v_div_fmas_f32 v51, v51, v52, v54
	v_div_fixup_f32 v29, v51, v50, v29
	ds_write_b32 v2, v29 offset:43008
	s_waitcnt vmcnt(17)
	v_mul_f32_e32 v50, 0xbfb8aa3b, v30
	v_exp_f32_e32 v50, v50
	s_nop 0
	v_add_f32_e32 v50, 1.0, v50
	v_div_scale_f32 v51, s[8:9], v50, v50, v30
	v_rcp_f32_e32 v52, v51
	v_div_scale_f32 v53, vcc, v30, v50, v30
	v_fma_f32 v54, -v51, v52, 1.0
	v_fmac_f32_e32 v52, v54, v52
	v_mul_f32_e32 v54, v53, v52
	v_fma_f32 v55, -v51, v54, v53
	v_fmac_f32_e32 v54, v55, v52
	v_fma_f32 v51, -v51, v54, v53
	v_div_fmas_f32 v51, v51, v52, v54
	v_div_fixup_f32 v30, v51, v50, v30
	ds_write_b32 v2, v30 offset:45056
	s_waitcnt vmcnt(16)
	v_mul_f32_e32 v50, 0xbfb8aa3b, v31
	v_exp_f32_e32 v50, v50
	s_nop 0
	v_add_f32_e32 v50, 1.0, v50
	v_div_scale_f32 v51, s[8:9], v50, v50, v31
	v_rcp_f32_e32 v52, v51
	v_div_scale_f32 v53, vcc, v31, v50, v31
	v_fma_f32 v54, -v51, v52, 1.0
	v_fmac_f32_e32 v52, v54, v52
	v_mul_f32_e32 v54, v53, v52
	v_fma_f32 v55, -v51, v54, v53
	v_fmac_f32_e32 v54, v55, v52
	v_fma_f32 v51, -v51, v54, v53
	v_div_fmas_f32 v51, v51, v52, v54
	v_div_fixup_f32 v31, v51, v50, v31
	ds_write_b32 v2, v31 offset:47104
	s_waitcnt vmcnt(15)
	v_mul_f32_e32 v50, 0xbfb8aa3b, v32
	v_exp_f32_e32 v50, v50
	s_nop 0
	v_add_f32_e32 v50, 1.0, v50
	v_div_scale_f32 v51, s[8:9], v50, v50, v32
	v_rcp_f32_e32 v52, v51
	v_div_scale_f32 v53, vcc, v32, v50, v32
	v_fma_f32 v54, -v51, v52, 1.0
	v_fmac_f32_e32 v52, v54, v52
	v_mul_f32_e32 v54, v53, v52
	v_fma_f32 v55, -v51, v54, v53
	v_fmac_f32_e32 v54, v55, v52
	v_fma_f32 v51, -v51, v54, v53
	v_div_fmas_f32 v51, v51, v52, v54
	v_div_fixup_f32 v32, v51, v50, v32
	ds_write_b32 v2, v32 offset:49152
	s_waitcnt vmcnt(14)
	v_mul_f32_e32 v50, 0xbfb8aa3b, v33
	v_exp_f32_e32 v50, v50
	s_nop 0
	v_add_f32_e32 v50, 1.0, v50
	v_div_scale_f32 v51, s[8:9], v50, v50, v33
	v_rcp_f32_e32 v52, v51
	v_div_scale_f32 v53, vcc, v33, v50, v33
	v_fma_f32 v54, -v51, v52, 1.0
	v_fmac_f32_e32 v52, v54, v52
	v_mul_f32_e32 v54, v53, v52
	v_fma_f32 v55, -v51, v54, v53
	v_fmac_f32_e32 v54, v55, v52
	v_fma_f32 v51, -v51, v54, v53
	v_div_fmas_f32 v51, v51, v52, v54
	v_div_fixup_f32 v33, v51, v50, v33
	ds_write_b32 v2, v33 offset:51200
	s_waitcnt vmcnt(13)
	v_mul_f32_e32 v50, 0xbfb8aa3b, v34
	v_exp_f32_e32 v50, v50
	s_nop 0
	v_add_f32_e32 v50, 1.0, v50
	v_div_scale_f32 v51, s[8:9], v50, v50, v34
	v_rcp_f32_e32 v52, v51
	v_div_scale_f32 v53, vcc, v34, v50, v34
	v_fma_f32 v54, -v51, v52, 1.0
	v_fmac_f32_e32 v52, v54, v52
	v_mul_f32_e32 v54, v53, v52
	v_fma_f32 v55, -v51, v54, v53
	v_fmac_f32_e32 v54, v55, v52
	v_fma_f32 v51, -v51, v54, v53
	v_div_fmas_f32 v51, v51, v52, v54
	v_div_fixup_f32 v34, v51, v50, v34
	ds_write_b32 v2, v34 offset:53248
	s_waitcnt vmcnt(12)
	v_mul_f32_e32 v50, 0xbfb8aa3b, v35
	v_exp_f32_e32 v50, v50
	s_nop 0
	v_add_f32_e32 v50, 1.0, v50
	v_div_scale_f32 v51, s[8:9], v50, v50, v35
	v_rcp_f32_e32 v52, v51
	v_div_scale_f32 v53, vcc, v35, v50, v35
	v_fma_f32 v54, -v51, v52, 1.0
	v_fmac_f32_e32 v52, v54, v52
	v_mul_f32_e32 v54, v53, v52
	v_fma_f32 v55, -v51, v54, v53
	v_fmac_f32_e32 v54, v55, v52
	v_fma_f32 v51, -v51, v54, v53
	v_div_fmas_f32 v51, v51, v52, v54
	v_div_fixup_f32 v35, v51, v50, v35
	ds_write_b32 v2, v35 offset:55296
	s_waitcnt vmcnt(11)
	v_mul_f32_e32 v50, 0xbfb8aa3b, v36
	v_exp_f32_e32 v50, v50
	s_nop 0
	v_add_f32_e32 v50, 1.0, v50
	v_div_scale_f32 v51, s[8:9], v50, v50, v36
	v_rcp_f32_e32 v52, v51
	v_div_scale_f32 v53, vcc, v36, v50, v36
	v_fma_f32 v54, -v51, v52, 1.0
	v_fmac_f32_e32 v52, v54, v52
	v_mul_f32_e32 v54, v53, v52
	v_fma_f32 v55, -v51, v54, v53
	v_fmac_f32_e32 v54, v55, v52
	v_fma_f32 v51, -v51, v54, v53
	v_div_fmas_f32 v51, v51, v52, v54
	v_div_fixup_f32 v36, v51, v50, v36
	ds_write_b32 v2, v36 offset:57344
	s_waitcnt vmcnt(10)
	v_mul_f32_e32 v50, 0xbfb8aa3b, v37
	v_exp_f32_e32 v50, v50
	s_nop 0
	v_add_f32_e32 v50, 1.0, v50
	v_div_scale_f32 v51, s[8:9], v50, v50, v37
	v_rcp_f32_e32 v52, v51
	v_div_scale_f32 v53, vcc, v37, v50, v37
	v_fma_f32 v54, -v51, v52, 1.0
	v_fmac_f32_e32 v52, v54, v52
	v_mul_f32_e32 v54, v53, v52
	v_fma_f32 v55, -v51, v54, v53
	v_fmac_f32_e32 v54, v55, v52
	v_fma_f32 v51, -v51, v54, v53
	v_div_fmas_f32 v51, v51, v52, v54
	v_div_fixup_f32 v37, v51, v50, v37
	ds_write_b32 v2, v37 offset:59392
	s_waitcnt vmcnt(9)
	v_mul_f32_e32 v50, 0xbfb8aa3b, v38
	v_exp_f32_e32 v50, v50
	s_nop 0
	v_add_f32_e32 v50, 1.0, v50
	v_div_scale_f32 v51, s[8:9], v50, v50, v38
	v_rcp_f32_e32 v52, v51
	v_div_scale_f32 v53, vcc, v38, v50, v38
	v_fma_f32 v54, -v51, v52, 1.0
	v_fmac_f32_e32 v52, v54, v52
	v_mul_f32_e32 v54, v53, v52
	v_fma_f32 v55, -v51, v54, v53
	v_fmac_f32_e32 v54, v55, v52
	v_fma_f32 v51, -v51, v54, v53
	v_div_fmas_f32 v51, v51, v52, v54
	v_div_fixup_f32 v38, v51, v50, v38
	ds_write_b32 v2, v38 offset:61440
	s_waitcnt vmcnt(8)
	v_mul_f32_e32 v50, 0xbfb8aa3b, v39
	v_exp_f32_e32 v50, v50
	s_nop 0
	v_add_f32_e32 v50, 1.0, v50
	v_div_scale_f32 v51, s[8:9], v50, v50, v39
	v_rcp_f32_e32 v52, v51
	v_div_scale_f32 v53, vcc, v39, v50, v39
	v_fma_f32 v54, -v51, v52, 1.0
	v_fmac_f32_e32 v52, v54, v52
	v_mul_f32_e32 v54, v53, v52
	v_fma_f32 v55, -v51, v54, v53
	v_fmac_f32_e32 v54, v55, v52
	v_fma_f32 v51, -v51, v54, v53
	v_div_fmas_f32 v51, v51, v52, v54
	v_div_fixup_f32 v39, v51, v50, v39
	ds_write_b32 v2, v39 offset:63488
	s_waitcnt vmcnt(7)
	v_mul_f32_e32 v50, 0xbfb8aa3b, v40
	v_exp_f32_e32 v50, v50
	s_nop 0
	v_add_f32_e32 v50, 1.0, v50
	v_div_scale_f32 v51, s[8:9], v50, v50, v40
	v_rcp_f32_e32 v52, v51
	v_div_scale_f32 v53, vcc, v40, v50, v40
	v_fma_f32 v54, -v51, v52, 1.0
	v_fmac_f32_e32 v52, v54, v52
	v_mul_f32_e32 v54, v53, v52
	v_fma_f32 v55, -v51, v54, v53
	v_fmac_f32_e32 v54, v55, v52
	v_fma_f32 v51, -v51, v54, v53
	v_div_fmas_f32 v51, v51, v52, v54
	v_div_fixup_f32 v40, v51, v50, v40
	ds_write_b32 v3, v40
	s_waitcnt vmcnt(6)
	v_mul_f32_e32 v50, 0xbfb8aa3b, v41
	v_exp_f32_e32 v50, v50
	s_nop 0
	v_add_f32_e32 v50, 1.0, v50
	v_div_scale_f32 v51, s[8:9], v50, v50, v41
	v_rcp_f32_e32 v52, v51
	v_div_scale_f32 v53, vcc, v41, v50, v41
	v_fma_f32 v54, -v51, v52, 1.0
	v_fmac_f32_e32 v52, v54, v52
	v_mul_f32_e32 v54, v53, v52
	v_fma_f32 v55, -v51, v54, v53
	v_fmac_f32_e32 v54, v55, v52
	v_fma_f32 v51, -v51, v54, v53
	v_div_fmas_f32 v51, v51, v52, v54
	v_div_fixup_f32 v41, v51, v50, v41
	ds_write_b32 v3, v41 offset:2048
	s_waitcnt vmcnt(5)
	v_mul_f32_e32 v50, 0xbfb8aa3b, v42
	v_exp_f32_e32 v50, v50
	s_nop 0
	v_add_f32_e32 v50, 1.0, v50
	v_div_scale_f32 v51, s[8:9], v50, v50, v42
	v_rcp_f32_e32 v52, v51
	v_div_scale_f32 v53, vcc, v42, v50, v42
	v_fma_f32 v54, -v51, v52, 1.0
	v_fmac_f32_e32 v52, v54, v52
	v_mul_f32_e32 v54, v53, v52
	v_fma_f32 v55, -v51, v54, v53
	v_fmac_f32_e32 v54, v55, v52
	v_fma_f32 v51, -v51, v54, v53
	v_div_fmas_f32 v51, v51, v52, v54
	v_div_fixup_f32 v42, v51, v50, v42
	ds_write_b32 v3, v42 offset:4096
	s_waitcnt vmcnt(4)
	v_mul_f32_e32 v50, 0xbfb8aa3b, v43
	v_exp_f32_e32 v50, v50
	s_nop 0
	v_add_f32_e32 v50, 1.0, v50
	v_div_scale_f32 v51, s[8:9], v50, v50, v43
	v_rcp_f32_e32 v52, v51
	v_div_scale_f32 v53, vcc, v43, v50, v43
	v_fma_f32 v54, -v51, v52, 1.0
	v_fmac_f32_e32 v52, v54, v52
	v_mul_f32_e32 v54, v53, v52
	v_fma_f32 v55, -v51, v54, v53
	v_fmac_f32_e32 v54, v55, v52
	v_fma_f32 v51, -v51, v54, v53
	v_div_fmas_f32 v51, v51, v52, v54
	v_div_fixup_f32 v43, v51, v50, v43
	ds_write_b32 v3, v43 offset:6144
	s_waitcnt vmcnt(3)
	v_mul_f32_e32 v50, 0xbfb8aa3b, v44
	v_exp_f32_e32 v50, v50
	s_nop 0
	v_add_f32_e32 v50, 1.0, v50
	v_div_scale_f32 v51, s[8:9], v50, v50, v44
	v_rcp_f32_e32 v52, v51
	v_div_scale_f32 v53, vcc, v44, v50, v44
	v_fma_f32 v54, -v51, v52, 1.0
	v_fmac_f32_e32 v52, v54, v52
	v_mul_f32_e32 v54, v53, v52
	v_fma_f32 v55, -v51, v54, v53
	v_fmac_f32_e32 v54, v55, v52
	v_fma_f32 v51, -v51, v54, v53
	v_div_fmas_f32 v51, v51, v52, v54
	v_div_fixup_f32 v44, v51, v50, v44
	ds_write_b32 v3, v44 offset:8192
	s_waitcnt vmcnt(2)
	v_mul_f32_e32 v50, 0xbfb8aa3b, v45
	v_exp_f32_e32 v50, v50
	s_nop 0
	v_add_f32_e32 v50, 1.0, v50
	v_div_scale_f32 v51, s[8:9], v50, v50, v45
	v_rcp_f32_e32 v52, v51
	v_div_scale_f32 v53, vcc, v45, v50, v45
	v_fma_f32 v54, -v51, v52, 1.0
	v_fmac_f32_e32 v52, v54, v52
	v_mul_f32_e32 v54, v53, v52
	v_fma_f32 v55, -v51, v54, v53
	v_fmac_f32_e32 v54, v55, v52
	v_fma_f32 v51, -v51, v54, v53
	v_div_fmas_f32 v51, v51, v52, v54
	v_div_fixup_f32 v45, v51, v50, v45
	ds_write_b32 v3, v45 offset:10240
	s_waitcnt vmcnt(1)
	v_mul_f32_e32 v50, 0xbfb8aa3b, v46
	v_exp_f32_e32 v50, v50
	s_nop 0
	v_add_f32_e32 v50, 1.0, v50
	v_div_scale_f32 v51, s[8:9], v50, v50, v46
	v_rcp_f32_e32 v52, v51
	v_div_scale_f32 v53, vcc, v46, v50, v46
	v_fma_f32 v54, -v51, v52, 1.0
	v_fmac_f32_e32 v52, v54, v52
	v_mul_f32_e32 v54, v53, v52
	v_fma_f32 v55, -v51, v54, v53
	v_fmac_f32_e32 v54, v55, v52
	v_fma_f32 v51, -v51, v54, v53
	v_div_fmas_f32 v51, v51, v52, v54
	v_div_fixup_f32 v46, v51, v50, v46
	ds_write_b32 v3, v46 offset:12288
	s_waitcnt vmcnt(0)
	v_mul_f32_e32 v50, 0xbfb8aa3b, v47
	v_exp_f32_e32 v50, v50
	s_nop 0
	v_add_f32_e32 v50, 1.0, v50
	v_div_scale_f32 v51, s[8:9], v50, v50, v47
	v_rcp_f32_e32 v52, v51
	v_div_scale_f32 v53, vcc, v47, v50, v47
	v_fma_f32 v54, -v51, v52, 1.0
	v_fmac_f32_e32 v52, v54, v52
	v_mul_f32_e32 v54, v53, v52
	v_fma_f32 v55, -v51, v54, v53
	v_fmac_f32_e32 v54, v55, v52
	v_fma_f32 v51, -v51, v54, v53
	v_div_fmas_f32 v51, v51, v52, v54
	v_div_fixup_f32 v47, v51, v50, v47
	ds_write_b32 v3, v47 offset:14336

.LBB0_179:
	s_add_u32 s0, s50, 0x21e00000
	s_addc_u32 s1, s51, 0
	v_writelane_b32 v249, s0, 53
	s_cmp_lt_i32 s68, 3
	s_nop 0
	v_writelane_b32 v249, s1, 54
	s_cselect_b64 s[0:1], -1, 0
	s_cmp_gt_i32 s69, 2
	s_cselect_b64 s[2:3], -1, 0
	s_and_b64 s[0:1], s[0:1], s[2:3]
	v_writelane_b32 v249, s68, 55
	s_andn2_b64 vcc, exec, s[0:1]
	s_nop 0
	v_writelane_b32 v249, s69, 56
	v_writelane_b32 v249, s70, 57
	s_cbranch_vccnz .LBB0_315
	s_cmp_lg_u32 s68, 0
	s_mov_b32 s18, 0
	s_cbranch_scc1 .LBB0_183
	s_abs_i32 s0, s92
	v_cvt_f32_u32_e32 v1, s0
	s_sub_i32 s1, 0, s0
	v_rcp_iflag_f32_e32 v1, v1
	s_nop 0
	v_mul_f32_e32 v1, 0x4f7ffffe, v1
	v_cvt_u32_f32_e32 v1, v1
	s_nop 0
	v_readfirstlane_b32 s2, v1
	s_mul_i32 s1, s1, s2
	s_mul_hi_u32 s1, s2, s1
	s_add_i32 s2, s2, s1
	s_mul_hi_u32 s1, s2, 0x900
	s_mul_i32 s1, s1, s0
	s_sub_i32 s1, 0x900, s1
	s_sub_i32 s2, s1, s0
	s_cmp_ge_u32 s1, s0
	s_cselect_b32 s1, s2, s1
	s_sub_i32 s2, s1, s0
	s_cmp_ge_u32 s1, s0
	s_cselect_b32 s0, s2, s1
	s_cmp_lg_u32 s0, 0
	s_cbranch_scc1 .LBB0_183
	s_add_i32 s0, 0, 0x20160
	v_mov_b32_e32 v1, s0
	ds_read_b32 v1, v1
	s_waitcnt lgkmcnt(0)
	s_mov_b32 s18, 0

.LBB0_488:
	s_add_u32 s96, s50, 0x40600000
	s_addc_u32 s97, s51, 0
	s_cmp_lt_i32 s68, 6
	s_cselect_b64 s[2:3], -1, 0
	s_cmp_gt_i32 s69, 5
	s_cselect_b64 s[4:5], -1, 0
	s_and_b64 s[2:3], s[2:3], s[4:5]
	s_andn2_b64 vcc, exec, s[2:3]
	s_cbranch_vccnz .LBB0_628
	s_cmp_lg_u32 s68, 0
	s_mov_b32 s33, 0
	s_cbranch_scc1 .LBB0_492
	s_abs_i32 s2, s92
	v_cvt_f32_u32_e32 v1, s2
	s_sub_i32 s3, 0, s2
	v_rcp_iflag_f32_e32 v1, v1
	s_nop 0
	v_mul_f32_e32 v1, 0x4f7ffffe, v1
	v_cvt_u32_f32_e32 v1, v1
	s_nop 0
	v_readfirstlane_b32 s4, v1
	s_mul_i32 s3, s3, s4
	s_mul_hi_u32 s3, s4, s3
	s_add_i32 s4, s4, s3
	s_mul_hi_u32 s3, s4, 0x300
	s_mul_i32 s3, s3, s2
	s_sub_i32 s3, 0x300, s3
	s_sub_i32 s4, s3, s2
	s_cmp_ge_u32 s3, s2
	s_cselect_b32 s3, s4, s3
	s_sub_i32 s4, s3, s2
	s_cmp_ge_u32 s3, s2
	s_cselect_b32 s2, s4, s3
	s_cmp_lg_u32 s2, 0
	s_cbranch_scc1 .LBB0_492
	s_add_i32 s2, 0, 0x20160
	v_mov_b32_e32 v1, s2
	ds_read_b32 v1, v1
	s_waitcnt lgkmcnt(0)
	s_mov_b32 s33, 0

.LBB0_726:
	s_cmp_lt_i32 s68, 8
	s_cselect_b64 s[0:1], -1, 0
	s_cmp_gt_i32 s69, 7
	s_cselect_b64 s[2:3], -1, 0
	s_and_b64 s[0:1], s[0:1], s[2:3]
	s_andn2_b64 vcc, exec, s[0:1]
	s_cbranch_vccnz .LBB0_863
	s_cmp_lg_u32 s68, 0
	s_mov_b32 s33, 0
	s_cbranch_scc1 .LBB0_730
	s_abs_i32 s0, s92
	v_cvt_f32_u32_e32 v1, s0
	s_sub_i32 s1, 0, s0
	v_rcp_iflag_f32_e32 v1, v1
	s_nop 0
	v_mul_f32_e32 v1, 0x4f7ffffe, v1
	v_cvt_u32_f32_e32 v1, v1
	s_nop 0
	v_readfirstlane_b32 s2, v1
	s_mul_i32 s1, s1, s2
	s_mul_hi_u32 s1, s2, s1
	s_add_i32 s2, s2, s1
	s_mul_hi_u32 s1, s2, 0xc00
	s_mul_i32 s1, s1, s0
	s_sub_i32 s1, 0xc00, s1
	s_sub_i32 s2, s1, s0
	s_cmp_ge_u32 s1, s0
	s_cselect_b32 s1, s2, s1
	s_sub_i32 s2, s1, s0
	s_cmp_ge_u32 s1, s0
	s_cselect_b32 s0, s2, s1
	s_cmp_lg_u32 s0, 0
	s_cbranch_scc1 .LBB0_730
	s_add_i32 s0, 0, 0x20160
	v_mov_b32_e32 v1, s0
	ds_read_b32 v1, v1
	s_waitcnt lgkmcnt(0)
	s_mov_b32 s33, 0

.LBB0_863:
	s_cmp_lt_i32 s68, 9
	s_cselect_b64 s[0:1], -1, 0
	s_cmp_gt_i32 s69, 8
	s_cselect_b64 s[2:3], -1, 0
	s_and_b64 s[0:1], s[0:1], s[2:3]
	s_andn2_b64 vcc, exec, s[0:1]
	s_cbranch_vccnz .LBB0_945
	s_cmp_lg_u32 s68, 0
	s_mov_b32 s19, 0
	s_cbranch_scc1 .LBB0_867
	s_abs_i32 s0, s92
	v_cvt_f32_u32_e32 v1, s0
	s_sub_i32 s1, 0, s0
	v_rcp_iflag_f32_e32 v1, v1
	s_nop 0
	v_mul_f32_e32 v1, 0x4f7ffffe, v1
	v_cvt_u32_f32_e32 v1, v1
	s_nop 0
	v_readfirstlane_b32 s2, v1
	s_mul_i32 s1, s1, s2
	s_mul_hi_u32 s1, s2, s1
	s_add_i32 s2, s2, s1
	s_mul_hi_u32 s1, s2, 0x300
	s_mul_i32 s1, s1, s0
	s_sub_i32 s1, 0x300, s1
	s_sub_i32 s2, s1, s0
	s_cmp_ge_u32 s1, s0
	s_cselect_b32 s1, s2, s1
	s_sub_i32 s2, s1, s0
	s_cmp_ge_u32 s1, s0
	s_cselect_b32 s0, s2, s1
	s_cmp_lg_u32 s0, 0
	s_cbranch_scc1 .LBB0_867
	s_add_i32 s0, 0, 0x20160
	v_mov_b32_e32 v1, s0
	ds_read_b32 v1, v1
	s_waitcnt lgkmcnt(0)
	s_mov_b32 s19, 0
